# v26 + fox first-tile K/V address setup and loads hoisted above the q-load wait (two round trips overlap)
# speedup vs baseline: 1.0124x; 1.0124x over previous
; #define LAS __attribute__((address_space(3)))
; DI float bf2f(unsigned h) { return __uint_as_float(h << 16); }
; DI void fox_unit(const bf16* PR, const float* AUX, const float* bfp, bf16* MIX, char* sm, int b, int h, int qb, bool do_cs) {
;     ...
;     const int t = q0 + 32 * wid + r32;
;     bf16x8 qr[5];
; #pragma unroll
;     for (int d0 = 0; d0 < 4; ++d0) qr[d0] = *(const bf16x8*)(PR + (rb + t) * NP + C_FQ + 64 * h + 16 * d0 + 8 * hi);
;     { const short one = hi ? (short)0 : (short)0x3F80; qr[4] = (bf16x8){one, one, one, 0, 0, 0, 0, 0}; }
;     const float cref = cbuf[q0];
;     const bf16* Kb = PR + rb * NP + C_FK + 64 * h; const bf16* Vb = PR + rb * NP + C_FV + 64 * h;
;     float m = MINIT, l = 0.f; f32x16 o0, o1;
; #pragma unroll
;     for (int i = 0; i < 16; ++i) { o0[i] = 0.f; o1[i] = 0.f; }
;     unsigned z_ = 0u; asm volatile("" : "+v"(z_)); u32x4 kr, vr, ar = {z_, z_, z_, z_};
;     const int wq0 = q0 + 32 * wid;
;     u32x4 zpre[4];
;     const bf16* zrow0 = PR + (rb + wq0) * NP + C_FZ + 64 * h;
;     float q1 = 0.f;
; #pragma unroll
;     for (int d0 = 0; d0 < 4; ++d0)
; #pragma unroll
;         for (int j = 0; j < 8; ++j) q1 += fabsf(bf2f((unsigned)(unsigned short)qr[d0][j]));
;     q1 += __shfl_xor(q1, 32);
;     volatile LAS unsigned* kmx = (volatile LAS unsigned*)(sm + L_MISC) + 32;
;     for (int it_ = -1, nt_ = (4 * qb + 4); it_ < nt_; ++it_) {
;         const bool more_ = it_ + 1 < nt_;
;         if (!more_) {
; #pragma unroll
;             for (int j = 0; j < 4; ++j) zpre[j] = *(const u32x4*)(zrow0 + (size_t)((lane >> 3) + 8 * j) * NP + 8 * (lane & 7));
;         }
;         if (more_) { const int kt = nt_ - 2 - it_; { kv_issue(Kb + (size_t)(64 * kt) * NP, Vb + (size_t)(64 * kt) * NP, NP, wid, lane, kr, vr);
;           if (wid == 0) ar = split3(8.f * (cref - cbuf[64 * kt + lane])); } }
.LBB0_304:
	v_lshlrev_b32_e32 v194, 4, v170
	s_lshl_b32 s20, s27, 5
	v_and_b32_e32 v6, 31, v170
	v_add_u32_e32 v7, 0, v194
	v_pk_add_f32 v[2:3], v[2:3], v[0:1] op_sel_hi:[1,0]
	v_pk_add_f32 v[4:5], v[4:5], v[0:1] op_sel_hi:[1,0]
	s_add_i32 s28, s20, s26
	ds_write_b128 v7, v[2:5] offset:36864
	v_or_b32_e32 v2, s28, v6
	s_sext_i32_i16 s8, s8
	v_ashrrev_i32_e32 v3, 31, v2
	v_lshl_add_u64 v[2:3], s[14:15], 0, v[2:3]
	s_lshl_b32 s8, s8, 6
	v_lshlrev_b64 v[2:3], 13, v[2:3]
	s_ashr_i32 s9, s8, 31
	v_lshrrev_b32_e32 v193, 5, v171
	v_lshl_add_u64 v[2:3], s[86:87], 0, v[2:3]
	s_lshl_b64 s[8:9], s[8:9], 1
	v_lshl_add_u64 v[2:3], v[2:3], 0, s[8:9]
	v_lshlrev_b32_e32 v0, 4, v193
	v_lshl_add_u64 v[2:3], v[2:3], 0, v[0:1]
	s_waitcnt lgkmcnt(0)
	s_barrier
	global_load_dwordx4 v[66:69], v[2:3], off
	global_load_dwordx4 v[70:73], v[2:3], off offset:32
	global_load_dwordx4 v[74:77], v[2:3], off offset:64
	global_load_dwordx4 v[78:81], v[2:3], off offset:96
	s_lshl_b32 s16, s26, 2
	s_add_i32 s16, s16, 0
	v_mov_b32_e32 v0, s16
	ds_read_b32 v195, v0 offset:36864
	s_lshl_b64 s[4:5], s[4:5], 24
	s_add_u32 s4, s86, s4
	s_addc_u32 s5, s87, s5
	s_add_u32 s16, s4, s8
	s_addc_u32 s17, s5, s9
	s_lshl_b32 s4, s27, 3
	s_ashr_i32 s5, s4, 31
	v_mov_b32_e32 v82, v1
	v_lshl_add_u32 v5, v171, 2, 0
	v_mov_b32_e32 v251, 0
	v_bfe_u32 v250, v171, 2, 3
	v_lshl_add_u32 v250, s27, 3, v250
	v_lshrrev_b32_e32 v246, 5, v171
	v_and_b32_e32 v247, 3, v171
	v_lshl_or_b32 v246, v246, 2, v247
	v_lshlrev_b32_e32 v247, 4, v250
	v_lshlrev_b32_e32 v250, 13, v250
	v_lshl_add_u32 v250, v246, 4, v250
	v_lshl_add_u32 v246, v246, 10, v247
	v_lshl_add_u64 v[146:147], s[16:17], 0, v[250:251]
	s_lshl_b32 s5, s27, 4
	v_lshrrev_b32_e32 v250, 2, v171
	v_and_or_b32 v250, s5, 48, v250
	s_andn2_b32 s4, s4, 31
	v_lshlrev_b32_e32 v250, 13, v250
	s_ashr_i32 s5, s4, 31
	v_lshl_add_u64 v[248:249], s[16:17], 0, v[250:251]
	s_cmp_lt_u32 s18, 64
	v_lshl_add_u64 v[248:249], s[4:5], 1, v[248:249]
	v_lshlrev_b32_e32 v250, 3, v171
	s_cselect_b64 s[18:19], -1, 0
	s_or_b32 s4, s26, 0xc0
	v_and_b32_e32 v196, 24, v250
	s_ashr_i32 s5, s4, 31
	v_lshlrev_b32_e32 v250, 1, v196
	s_lshl_b64 s[4:5], s[4:5], 13
	v_lshl_add_u64 v[158:159], v[248:249], 0, v[250:251]
	v_lshl_add_u64 v[248:249], v[146:147], 0, s[4:5]
	global_load_dwordx4 v[90:93], v[248:249], off offset:768
	v_lshl_add_u64 v[248:249], v[158:159], 0, s[4:5]
	global_load_dwordx4 v[94:97], v[248:249], off offset:1536
	s_waitcnt vmcnt(5)
	v_lshlrev_b32_e32 v0, 16, v66
	v_and_b32_e32 v2, 0xffff0000, v66
	v_add_f32_e64 v0, |v0|, |v2|
	v_lshlrev_b32_e32 v2, 16, v67
	v_add_f32_e64 v0, |v2|, v0
	v_and_b32_e32 v2, 0xffff0000, v67
	v_add_f32_e64 v0, |v2|, v0
	v_lshlrev_b32_e32 v2, 16, v68
	v_add_f32_e64 v0, |v2|, v0
	v_and_b32_e32 v2, 0xffff0000, v68
	v_add_f32_e64 v0, |v2|, v0
	v_lshlrev_b32_e32 v2, 16, v69
	v_add_f32_e64 v0, |v2|, v0
	v_and_b32_e32 v2, 0xffff0000, v69
	v_add_f32_e64 v0, |v2|, v0
	s_waitcnt vmcnt(4)
	v_lshlrev_b32_e32 v2, 16, v70
	v_add_f32_e64 v0, |v2|, v0
	v_and_b32_e32 v2, 0xffff0000, v70
	v_add_f32_e64 v0, |v2|, v0
	v_lshlrev_b32_e32 v2, 16, v71
	v_add_f32_e64 v0, |v2|, v0
	v_and_b32_e32 v2, 0xffff0000, v71
	v_add_f32_e64 v0, |v2|, v0
	v_lshlrev_b32_e32 v2, 16, v72
	v_add_f32_e64 v0, |v2|, v0
	v_and_b32_e32 v2, 0xffff0000, v72
	v_add_f32_e64 v0, |v2|, v0
	v_lshlrev_b32_e32 v2, 16, v73
	v_add_f32_e64 v0, |v2|, v0
	v_and_b32_e32 v2, 0xffff0000, v73
	v_add_f32_e64 v0, |v2|, v0
	s_waitcnt vmcnt(3)
	v_lshlrev_b32_e32 v2, 16, v74
	v_add_f32_e64 v0, |v2|, v0
	v_and_b32_e32 v2, 0xffff0000, v74
	v_add_f32_e64 v0, |v2|, v0
	v_lshlrev_b32_e32 v2, 16, v75
	v_add_f32_e64 v0, |v2|, v0
	v_and_b32_e32 v2, 0xffff0000, v75
	v_add_f32_e64 v0, |v2|, v0
	v_lshlrev_b32_e32 v2, 16, v76
	v_add_f32_e64 v0, |v2|, v0
	v_and_b32_e32 v2, 0xffff0000, v76
	v_add_f32_e64 v0, |v2|, v0
	v_lshlrev_b32_e32 v2, 16, v77
	v_add_f32_e64 v0, |v2|, v0
	v_and_b32_e32 v2, 0xffff0000, v77
	v_add_f32_e64 v0, |v2|, v0
	s_waitcnt vmcnt(2)
	v_lshlrev_b32_e32 v2, 16, v78
	v_add_f32_e64 v0, |v2|, v0
	v_and_b32_e32 v2, 0xffff0000, v78
	v_add_f32_e64 v0, |v2|, v0
	v_lshlrev_b32_e32 v2, 16, v79
	v_add_f32_e64 v0, |v2|, v0
	v_and_b32_e32 v2, 0xffff0000, v79
	v_add_f32_e64 v0, |v2|, v0
	v_lshlrev_b32_e32 v2, 16, v80
	v_add_f32_e64 v0, |v2|, v0
	v_and_b32_e32 v2, 0xffff0000, v80
	v_add_f32_e64 v0, |v2|, v0
	v_lshlrev_b32_e32 v2, 16, v81
	v_add_f32_e64 v0, |v2|, v0
	v_and_b32_e32 v2, 0xffff0000, v81
	v_add_f32_e64 v3, |v2|, v0
	v_xor_b32_e32 v0, 32, v181
	v_add_u32_e32 v2, 64, v8
	v_cmp_lt_i32_e32 vcc, v0, v2
	s_nop 1
	v_cndmask_b32_e32 v0, v181, v0, vcc
	v_lshlrev_b32_e32 v187, 2, v0
	ds_bpermute_b32 v4, v187, v3
	s_and_b64 vcc, exec, s[18:19]
	s_cbranch_vccz .LBB0_336
	v_lshl_add_u32 v0, s26, 2, v5
	ds_read_b32 v0, v0 offset:37632
	v_mov_b32_e32 v84, 0
	s_waitcnt lgkmcnt(0)
	v_sub_f32_e32 v0, v195, v0
	v_mul_f32_e32 v8, 0x41000000, v0
	v_bfe_u32 v9, v8, 16, 1
	v_add3_u32 v8, v8, v9, s93
	v_and_b32_e32 v9, 0xffff0000, v8
	v_fma_f32 v0, v0, s59, -v9
	v_bfe_u32 v9, v0, 16, 1
	v_add3_u32 v9, v0, v9, s93
	v_and_b32_e32 v9, 0xffff0000, v9
	v_sub_f32_e32 v0, v0, v9
	v_or_b32_sdwa v82, v9, v8 dst_sel:DWORD dst_unused:UNUSED_PAD src0_sel:DWORD src1_sel:WORD_1
	v_bfe_u32 v8, v0, 16, 1
	v_add3_u32 v0, v0, v8, s93
	v_lshrrev_b32_e32 v83, 16, v0
	s_branch .LBB0_337
